# scan chunk loops: prefetch loads drained before the post-stage stores, chunk-top / preprocess vmcnt waits no longer wait for store acks (all four mixers)
# baseline (speedup 1.0000x reference)
; template <int MIX>
; __device__ __forceinline__ void scan_part(const Params& p, const int layer, const int smp, const int b0, const int bstep, const int bend, const int h, const int part, char* lds, const int tid) {
;     ...
;   } else {
;     gam = 1.0f - exp2f(-5.0f - (float)h);
;   }
;   for (int b = b0; b < bend; b += bstep) {
;     ...
;   __syncthreads();
;   int ntok_last = 0;
;   for (int t0 = 0; t0 < T; t0 += 32) {
.LBB0_312:
	s_or_b64 exec, exec, s[36:37]
	v_readlane_b32 s36, v254, 17
	v_cvt_f32_ubyte0_e32 v14, s25
	v_sub_f32_e32 v14, 0xc0a00000, v14
	s_mov_b32 s36, 0xc2fc0000
	v_readlane_b32 s37, v254, 18
	v_cmp_gt_f32_e32 vcc, s36, v14
	s_mov_b32 s43, s37
	s_mov_b32 s35, s37
	s_and_b64 s[36:37], vcc, exec
	s_cselect_b32 s36, 0xffffffc0, 0
	s_lshl_b64 s[38:39], s[34:35], 11
	s_add_u32 s35, s72, s38
	s_addc_u32 s40, s73, s39
	s_lshl_b32 s42, s29, 1
	v_writelane_b32 v254, s42, 17
	s_add_u32 s29, s35, s42
	s_addc_u32 s39, s40, 0
	s_lshl_b32 s38, s23, 1
	v_cndmask_b32_e32 v15, 0, v162, vcc
	s_add_u32 s38, s29, s38
	s_mul_hi_u32 s41, s34, 0xfffffa00
	v_add_f32_e32 v14, v14, v15
	s_addc_u32 s39, s39, 0
	s_mul_i32 s29, s34, 0xfffffa00
	s_sub_i32 s34, s41, s34
	v_exp_f32_e32 v14, v14
	s_add_u32 s29, s35, s29
	s_addc_u32 s34, s40, s34
	s_lshl_b32 s35, s25, 5
	s_add_u32 s29, s29, s35
	s_addc_u32 s34, s34, 0
	s_lshl_b32 s35, s26, 3
	v_lshlrev_b32_e32 v15, 2, v0
	v_bfe_u32 v13, v130, 3, 3
	v_ldexp_f32 v14, v14, s36
	s_add_u32 s29, s29, s35
	v_and_b32_e32 v15, 0xffffffe0, v15
	v_lshrrev_b32_e32 v1, 3, v130
	v_sub_f32_e32 v44, 1.0, v14
	v_lshlrev_b32_e32 v14, 4, v57
	v_lshlrev_b32_e32 v12, 2, v12
	s_addc_u32 s35, s34, 0
	v_lshl_add_u32 v16, v57, 7, v15
	v_lshlrev_b32_e32 v13, 2, v13
	v_bfi_b32 v1, -8, v0, v1
	v_sub_u32_e32 v14, v28, v14
	v_lshl_or_b32 v60, v0, 10, v12
	v_lshlrev_b32_e32 v12, 7, v0
	s_add_u32 s34, s29, 0x2255280
	v_mov_b32_e32 v33, v3
	v_or_b32_e32 v16, v16, v13
	v_or_b32_e32 v13, v15, v13
	v_lshlrev_b32_e32 v58, 3, v57
	v_lshlrev_b32_e32 v59, 2, v1
	v_cmp_eq_u32_e64 s[36:37], 0, v57
	v_writelane_b32 v254, s43, 18
	s_addc_u32 s35, s35, 0
	v_lshl_add_u64 v[46:47], s[38:39], 0, v[32:33]
	v_lshl_add_u64 v[48:49], s[74:75], 0, v[28:29]
	v_mov_b32_e32 v45, v44
	v_add_u32_e32 v29, 0x7d00, v16
	v_add_u32_e32 v61, 0x700, v13
	v_or_b32_e32 v62, 0x400, v28
	v_add_u32_e32 v63, v14, v12
	v_mov_b32_e32 v31, v30
	v_mov_b32_e32 v50, v30
	v_mov_b32_e32 v51, v30
	v_mov_b32_e32 v52, v30
	v_mov_b32_e32 v53, v30
	v_mov_b32_e32 v54, v30
	v_mov_b32_e32 v55, v30
	s_waitcnt vmcnt(0)
	s_barrier
	s_branch .LBB0_314

; __device__ __forceinline__ float bflo(unsigned u) { return __uint_as_float(u << 16); }
; __device__ __forceinline__ float bfhi(unsigned u) { return __uint_as_float(u & 0xffff0000u); }
; template <int MIX>
; __device__ __forceinline__ void scan_part(const Params& p, const int layer, const int smp, const int b0, const int bstep, const int bend, const int h, const int part, char* lds, const int tid) {
;     ...
;       if (valid) {
;         const float ql[4] = {bflo(R0.x), bfhi(R0.x), bflo(R0.y), bfhi(R0.y)}, qh[4] = {bflo(R0.z), bfhi(R0.z), bflo(R0.w), bfhi(R0.w)};
;         const float kl[4] = {bflo(R1.x), bfhi(R1.x), bflo(R1.y), bfhi(R1.y)}, kh[4] = {bflo(R1.z), bfhi(R1.z), bflo(R1.w), bfhi(R1.w)};
;         const float cc[4] = {__uint_as_float(R4.x), __uint_as_float(R4.z), __uint_as_float(R5.x), __uint_as_float(R5.z)};
;         const float sn[4] = {__uint_as_float(R4.y), __uint_as_float(R4.w), __uint_as_float(R5.y), __uint_as_float(R5.w)};
;         f32x4 qa, qb, ka, kb;
; #pragma unroll
;         for (int i = 0; i < 4; ++i) {
;           qa[i] = ql[i] * cc[i] - qh[i] * sn[i]; qb[i] = ql[i] * sn[i] + qh[i] * cc[i];
;           ka[i] = (kl[i] * cc[i] - kh[i] * sn[i]) * 0.125f; kb[i] = (kl[i] * sn[i] + kh[i] * cc[i]) * 0.125f;
;         }
;         *(f32x4*)(dst + sub * 4) = qa; *(f32x4*)(dst + 32 + sub * 4) = qb;
;         *(f32x4*)(dst + 64 + sub * 4) = ka; *(f32x4*)(dst + 96 + sub * 4) = kb;
;       }
.LBB0_314:
	s_mov_b32 s29, s27
	s_sub_i32 s27, 0x810, s27
	s_min_u32 s44, s27, 32
	v_cmp_gt_i32_e64 s[38:39], s44, v0
	s_and_saveexec_b64 s[40:41], s[38:39]
	s_cbranch_execz .LBB0_316
	s_waitcnt vmcnt(2)
	v_lshlrev_b32_e32 v12, 16, v34
	v_and_b32_e32 v13, 0xffff0000, v34
	v_lshlrev_b32_e32 v14, 16, v35
	v_and_b32_e32 v15, 0xffff0000, v35
	s_waitcnt vmcnt(2)
	v_lshlrev_b32_e32 v16, 16, v40
	v_and_b32_e32 v17, 0xffff0000, v40
	s_waitcnt vmcnt(2)
	v_mov_b32_e32 v18, v9
	v_mov_b32_e32 v19, v11
	v_mov_b32_e32 v20, v8
	v_mov_b32_e32 v21, v10
	ds_write_b128 v60, v[12:15] offset:768
	v_lshlrev_b32_e32 v14, 16, v38
	v_and_b32_e32 v15, 0xffff0000, v38
	v_pk_mul_f32 v[12:13], v[20:21], v[16:17]
	v_pk_mul_f32 v[16:17], v[18:19], v[16:17]
	v_pk_fma_f32 v[12:13], v[18:19], v[14:15], v[12:13]
	v_pk_fma_f32 v[16:17], v[20:21], v[14:15], v[16:17] neg_lo:[0,0,1] neg_hi:[0,0,1]
	v_lshlrev_b32_e32 v14, 16, v42
	v_and_b32_e32 v15, 0xffff0000, v36
	v_mov_b32_e32 v24, v8
	v_mov_b32_e32 v25, v11
	v_lshlrev_b32_e32 v22, 16, v36
	v_and_b32_e32 v23, 0xffff0000, v42
	v_pk_mul_f32 v[24:25], v[24:25], v[14:15]
	v_pk_mov_b32 v[26:27], v[8:9], v[10:11] op_sel:[1,0]
	v_mov_b32_e32 v64, v4
	v_pk_fma_f32 v[24:25], v[26:27], v[22:23], v[24:25]
	v_mov_b32_e32 v27, v15
	v_mov_b32_e32 v15, v23
	v_mov_b32_e32 v26, v22
	v_pk_mul_f32 v[14:15], v[18:19], v[14:15]
	v_lshlrev_b32_e32 v22, 16, v41
	v_pk_fma_f32 v[20:21], v[20:21], v[26:27], v[14:15] neg_lo:[0,0,1] neg_hi:[0,0,1]
	v_and_b32_e32 v23, 0xffff0000, v41
	v_mov_b32_e32 v26, v5
	v_mov_b32_e32 v27, v7
	v_mov_b32_e32 v65, v6
	v_lshlrev_b32_e32 v18, 16, v39
	v_and_b32_e32 v19, 0xffff0000, v39
	v_pk_mul_f32 v[14:15], v[64:65], v[22:23]
	v_pk_mul_f32 v[22:23], v[26:27], v[22:23]
	v_lshlrev_b32_e32 v66, 16, v43
	v_and_b32_e32 v67, 0xffff0000, v43
	v_pk_fma_f32 v[14:15], v[26:27], v[18:19], v[14:15]
	v_pk_fma_f32 v[18:19], v[64:65], v[18:19], v[22:23] neg_lo:[0,0,1] neg_hi:[0,0,1]
	v_lshlrev_b32_e32 v22, 16, v37
	v_and_b32_e32 v23, 0xffff0000, v37
	v_pk_mul_f32 v[68:69], v[64:65], v[66:67]
	s_mov_b32 s42, 0x3e000000
	v_pk_fma_f32 v[68:69], v[26:27], v[22:23], v[68:69]
	v_pk_mul_f32 v[26:27], v[26:27], v[66:67]
	v_pk_mul_f32 v[20:21], v[20:21], s[42:43] op_sel_hi:[1,0]
	v_pk_fma_f32 v[22:23], v[64:65], v[22:23], v[26:27] neg_lo:[0,0,1] neg_hi:[0,0,1]
	v_pk_mul_f32 v[24:25], v[24:25], s[42:43] op_sel_hi:[1,0]
	v_pk_mul_f32 v[22:23], v[22:23], s[42:43] op_sel_hi:[1,0]
	v_pk_mul_f32 v[26:27], v[68:69], s[42:43] op_sel_hi:[1,0]
	ds_write_b128 v60, v[16:19]
	ds_write_b128 v60, v[12:15] offset:128
	ds_write_b128 v60, v[20:23] offset:256
	ds_write_b128 v60, v[24:27] offset:384

; __device__ __forceinline__ unsigned pk2(float lo, float hi) { const f32x2_t v = {lo, hi}; const bf16x2_t b = __builtin_convertvector(v, bf16x2_t); return __builtin_bit_cast(unsigned, b); }
; __device__ __forceinline__ float red8d(float x) { x += dpp_x1(x); x += dpp_x2(x); x += dpp_hm(x); return x; }
; template <int MIX>
; __device__ __forceinline__ void scan_part(const Params& p, const int layer, const int smp, const int b0, const int bstep, const int bend, const int h, const int part, char* lds, const int tid) {
;     ...
;     __syncthreads();
;     if (valid) {
;       float o[VN];
; #pragma unroll
;       for (int i = 0; i < VN; ++i) o[i] = obuf[tt * CW + sub * VN + i];
;       float s1 = 0.f, s2 = 0.f;
; #pragma unroll
;       for (int i = 0; i < VN; ++i) { s1 += o[i]; s2 += o[i] * o[i]; }
;       s1 = red8d(s1); s2 = red8d(s2);
;       if (VN == 4) { uint2 o2; o2.x = pk2(o[0], o[1]); o2.y = pk2(o[2 % VN], o[3 % VN]); *(uint2*)(Ob + (size_t)(t0 + tt) * 1024 + sub * 4) = o2; }
;       else *(unsigned*)(Ob + (size_t)(t0 + tt) * 1024 + sub * 2) = pk2(o[0], o[1]);
;       if (sub == 0) *(float2*)(PS + (size_t)(t0 + tt) * 128) = make_float2(s1, s2);
;     }
.LBB0_324:
	s_waitcnt vmcnt(0) lgkmcnt(0)
	s_barrier
	s_and_saveexec_b64 s[42:43], s[38:39]
	s_cbranch_execz .LBB0_313
	ds_read_b128 v[16:19], v63 offset:32768
	s_waitcnt lgkmcnt(0)
	v_add_f32_e32 v15, 0, v16
	v_mul_f32_e32 v14, v16, v16
	v_mov_b32_e32 v12, v16
	v_mov_b32_e32 v13, v18
	v_add_f32_e32 v20, v15, v17
	v_fmac_f32_e32 v14, v17, v17
	v_mov_b32_e32 v21, v19
	v_pk_fma_f32 v[12:13], v[12:13], v[12:13], v[14:15] op_sel_hi:[1,1,0]
	v_pk_add_f32 v[14:15], v[20:21], v[18:19]
	v_pk_mul_f32 v[20:21], v[18:19], v[18:19]
	v_mov_b32_e32 v12, v19
	v_mov_b32_e32 v15, v21
	v_pk_add_f32 v[12:13], v[14:15], v[12:13]
	v_cvt_pk_bf16_f32 v20, v16, v17
	v_add_u32_e32 v16, s29, v0
	v_mov_b32_dpp v14, v12 quad_perm:[1,0,3,2] row_mask:0xf bank_mask:0xf bound_ctrl:1
	v_mov_b32_dpp v15, v13 quad_perm:[1,0,3,2] row_mask:0xf bank_mask:0xf bound_ctrl:1
	v_pk_add_f32 v[12:13], v[12:13], v[14:15]
	v_ashrrev_i32_e32 v17, 31, v16
	v_cvt_pk_bf16_f32 v21, v18, v19
	v_mov_b32_dpp v14, v12 quad_perm:[2,3,0,1] row_mask:0xf bank_mask:0xf bound_ctrl:1
	v_mov_b32_dpp v15, v13 quad_perm:[2,3,0,1] row_mask:0xf bank_mask:0xf bound_ctrl:1
	v_pk_add_f32 v[12:13], v[12:13], v[14:15]
	v_lshlrev_b64 v[18:19], 11, v[16:17]
	v_lshl_add_u64 v[18:19], v[46:47], 0, v[18:19]
	v_mov_b32_dpp v14, v12 row_half_mirror row_mask:0xf bank_mask:0xf bound_ctrl:1
	v_mov_b32_dpp v15, v13 row_half_mirror row_mask:0xf bank_mask:0xf bound_ctrl:1
	global_store_dwordx2 v[18:19], v[20:21], off offset:1536
	s_and_b64 exec, exec, s[36:37]
	s_cbranch_execz .LBB0_313
	v_lshlrev_b64 v[16:17], 9, v[16:17]
	v_lshl_add_u64 v[16:17], s[34:35], 0, v[16:17]
	v_pk_add_f32 v[12:13], v[12:13], v[14:15]
	global_store_dwordx2 v[16:17], v[12:13], off
	s_branch .LBB0_313

;   __device__ __forceinline__ const float* I(int i) const { return (const float*)(const GAS float*)in[i]; }
; template <int MIX>
; __device__ __forceinline__ void scan_part(const Params& p, const int layer, const int smp, const int b0, const int bstep, const int bend, const int h, const int part, char* lds, const int tid) {
;     ...
;   } else if (MIX == 2) {
;     for (int e = tid; e < 512; e += 256) { const int r = e >> 5, j = e & 31; wgl[e] = p.I(17)[(size_t)(layer * 16 + r) * 128 + h * 32 + j]; }
; #pragma unroll
;     for (int i = 0; i < 4; ++i) c8[i] = p.I(18)[layer * 128 + h * 32 + sub * 4 + i];
;     ...
;   __syncthreads();
;   int ntok_last = 0;
;   for (int t0 = 0; t0 < T; t0 += 32) {
.LBB0_350:
	s_or_b64 exec, exec, s[36:37]
	v_readlane_b32 s36, v254, 17
	v_readlane_b32 s37, v254, 18
	s_mov_b32 s35, s37
	s_lshl_b64 s[38:39], s[34:35], 11
	s_add_u32 s29, s72, s38
	s_mov_b32 s41, s37
	s_addc_u32 s35, s73, s39
	s_lshl_b32 s40, s27, 1
	v_writelane_b32 v254, s40, 17
	s_add_u32 s27, s29, s40
	s_addc_u32 s39, s35, 0
	s_lshl_b32 s38, s23, 1
	v_writelane_b32 v254, s41, 18
	s_add_u32 s38, s27, s38
	s_mul_hi_u32 s40, s34, 0xfffffa00
	s_addc_u32 s39, s39, 0
	s_mul_i32 s27, s34, 0xfffffa00
	s_sub_i32 s34, s40, s34
	s_add_u32 s27, s29, s27
	s_addc_u32 s29, s35, s34
	s_lshl_b32 s34, s25, 5
	s_add_u32 s27, s27, s34
	v_lshlrev_b32_e32 v18, 2, v45
	v_bfe_u32 v17, v130, 3, 3
	s_addc_u32 s29, s29, 0
	s_lshl_b32 s34, s26, 3
	v_and_b32_e32 v18, 0xffffffe0, v18
	s_add_u32 s27, s27, s34
	v_lshl_add_u32 v19, v43, 7, v18
	v_lshlrev_b32_e32 v17, 2, v17
	v_lshrrev_b32_e32 v16, 3, v130
	s_addc_u32 s29, s29, 0
	v_or_b32_e32 v19, v19, v17
	v_or_b32_e32 v17, v18, v17
	v_bfi_b32 v46, -8, v45, v16
	v_lshlrev_b32_e32 v47, 2, v44
	v_lshlrev_b32_e32 v16, 7, v45
	s_add_u32 s34, s27, 0x2255200
	v_mov_b32_e32 v31, v3
	v_add_u32_e32 v51, 0x700, v17
	v_mov_b32_e32 v17, 0x400
	v_lshlrev_b32_e32 v48, 2, v46
	v_lshl_or_b32 v49, v45, 10, v47
	v_cmp_eq_u32_e64 s[36:37], 0, v43
	s_addc_u32 s35, s29, 0
	v_lshl_add_u64 v[38:39], s[38:39], 0, v[30:31]
	v_add_u32_e32 v50, 0x7d00, v19
	v_lshl_or_b32 v52, v43, 4, v17
	v_add_u32_e32 v53, v47, v16
	v_mov_b32_e32 v29, v28
	v_mov_b32_e32 v40, v28
	v_mov_b32_e32 v41, v28
	s_waitcnt lgkmcnt(0)
	s_waitcnt vmcnt(0)
	s_barrier
	s_branch .LBB0_352

; __device__ __forceinline__ float bflo(unsigned u) { return __uint_as_float(u << 16); }
; __device__ __forceinline__ float bfhi(unsigned u) { return __uint_as_float(u & 0xffff0000u); }
; template <int MIX>
; __device__ __forceinline__ void scan_part(const Params& p, const int layer, const int smp, const int b0, const int bstep, const int bend, const int h, const int part, char* lds, const int tid) {
;     ...
;     } else if (MIX == 2) {
;       if (valid) {
;         float lr[16]; unpack8(R1, lr); unpack8(R4, lr + 8);
;         const float q0 = bflo(R0.x), q1 = bfhi(R0.x), q2 = bflo(R0.y), q3 = bfhi(R0.y);
;         const float k0 = bflo(R0.z), k1 = bfhi(R0.z), k2 = bflo(R0.w), k3 = bfhi(R0.w);
;         const float sc = 0.17677669529663687f;
;         f32x4 xg = (f32x4){c8[0], c8[1], c8[2], c8[3]};
; #pragma unroll
;         for (int r = 0; r < 16; ++r) xg += lr[r] * *(const f32x4*)(wgl + r * 32 + sub * 4);
.LBB0_352:
	s_sub_i32 s29, 0x810, s44
	s_min_u32 s29, s29, 32
	s_mov_b32 s27, s44
	v_cmp_gt_i32_e64 s[38:39], s29, v45
	s_and_saveexec_b64 s[42:43], s[38:39]
	s_cbranch_execz .LBB0_354
	ds_read_b128 v[54:57], v47 offset:37376
	s_waitcnt vmcnt(2)
	v_lshlrev_b32_e32 v58, 16, v12
	v_lshlrev_b32_e32 v16, 16, v32
	v_and_b32_e32 v17, 0xffff0000, v32
	v_lshlrev_b32_e32 v18, 16, v33
	s_waitcnt vmcnt(2) lgkmcnt(0)
	v_pk_fma_f32 v[80:81], v[58:59], v[56:57], v[6:7] op_sel_hi:[0,1,1]
	v_pk_fma_f32 v[58:59], v[58:59], v[54:55], v[4:5] op_sel_hi:[0,1,1]
	ds_read_b128 v[54:57], v47 offset:37504
	v_and_b32_e32 v19, 0xffff0000, v33
	ds_write_b128 v49, v[16:19] offset:768
	v_and_b32_e32 v60, 0xffff0000, v12
	v_lshlrev_b32_e32 v62, 16, v13
	s_waitcnt lgkmcnt(1)
	v_pk_fma_f32 v[80:81], v[60:61], v[56:57], v[80:81] op_sel_hi:[0,1,1]
	v_pk_fma_f32 v[58:59], v[60:61], v[54:55], v[58:59] op_sel_hi:[0,1,1]
	ds_read_b128 v[54:57], v47 offset:37632
	v_and_b32_e32 v64, 0xffff0000, v13
	v_lshlrev_b32_e32 v66, 16, v14
	v_and_b32_e32 v68, 0xffff0000, v14
	v_lshlrev_b32_e32 v70, 16, v15
	s_waitcnt lgkmcnt(0)
	v_pk_fma_f32 v[60:61], v[62:63], v[56:57], v[80:81] op_sel_hi:[0,1,1]
	v_pk_fma_f32 v[58:59], v[62:63], v[54:55], v[58:59] op_sel_hi:[0,1,1]
	ds_read_b128 v[54:57], v47 offset:37760
	v_and_b32_e32 v72, 0xffff0000, v15
	v_lshlrev_b32_e32 v74, 16, v8
	v_and_b32_e32 v76, 0xffff0000, v8
	v_lshlrev_b32_e32 v78, 16, v9
	s_waitcnt lgkmcnt(0)
	v_pk_fma_f32 v[60:61], v[64:65], v[56:57], v[60:61] op_sel_hi:[0,1,1]
	v_pk_fma_f32 v[58:59], v[64:65], v[54:55], v[58:59] op_sel_hi:[0,1,1]
	ds_read_b128 v[54:57], v47 offset:37888
	v_and_b32_e32 v42, 0xffff0000, v9
	v_lshlrev_b32_e32 v26, 16, v10
	v_and_b32_e32 v24, 0xffff0000, v10
	v_lshlrev_b32_e32 v22, 16, v11
	s_waitcnt lgkmcnt(0)
	v_pk_fma_f32 v[60:61], v[66:67], v[56:57], v[60:61] op_sel_hi:[0,1,1]
	v_pk_fma_f32 v[58:59], v[66:67], v[54:55], v[58:59] op_sel_hi:[0,1,1]
	ds_read_b128 v[54:57], v47 offset:38016
	v_and_b32_e32 v20, 0xffff0000, v11
	s_mov_b32 s44, 0xbfb8aa3b
	s_mov_b32 s45, 0x3f317217
	s_mov_b32 s46, 0x7f800000
	s_waitcnt lgkmcnt(0)
	v_pk_fma_f32 v[60:61], v[68:69], v[56:57], v[60:61] op_sel_hi:[0,1,1]
	v_pk_fma_f32 v[58:59], v[68:69], v[54:55], v[58:59] op_sel_hi:[0,1,1]
	ds_read_b128 v[54:57], v47 offset:38144
	v_lshlrev_b32_e32 v16, 16, v36
	v_lshlrev_b32_e32 v18, 16, v37
	v_and_b32_e32 v17, 0xffff0000, v36
	s_waitcnt lgkmcnt(0)
	v_pk_fma_f32 v[60:61], v[70:71], v[56:57], v[60:61] op_sel_hi:[0,1,1]
	v_pk_fma_f32 v[58:59], v[70:71], v[54:55], v[58:59] op_sel_hi:[0,1,1]
	ds_read_b128 v[54:57], v47 offset:38272
	s_waitcnt lgkmcnt(0)
	v_pk_fma_f32 v[60:61], v[72:73], v[56:57], v[60:61] op_sel_hi:[0,1,1]
	v_pk_fma_f32 v[58:59], v[72:73], v[54:55], v[58:59] op_sel_hi:[0,1,1]
	ds_read_b128 v[54:57], v47 offset:38400
	s_waitcnt lgkmcnt(0)
	v_pk_fma_f32 v[60:61], v[74:75], v[56:57], v[60:61] op_sel_hi:[0,1,1]
	v_pk_fma_f32 v[58:59], v[74:75], v[54:55], v[58:59] op_sel_hi:[0,1,1]
	ds_read_b128 v[54:57], v47 offset:38528
	s_waitcnt lgkmcnt(0)
	v_pk_fma_f32 v[60:61], v[76:77], v[56:57], v[60:61] op_sel_hi:[0,1,1]
	v_pk_fma_f32 v[58:59], v[76:77], v[54:55], v[58:59] op_sel_hi:[0,1,1]
	ds_read_b128 v[54:57], v47 offset:38656
	s_waitcnt lgkmcnt(0)
	v_pk_fma_f32 v[60:61], v[78:79], v[56:57], v[60:61] op_sel_hi:[0,1,1]
	v_pk_fma_f32 v[58:59], v[78:79], v[54:55], v[58:59] op_sel_hi:[0,1,1]
	ds_read_b128 v[54:57], v47 offset:38784
	s_waitcnt lgkmcnt(0)
	v_pk_fma_f32 v[60:61], v[42:43], v[56:57], v[60:61] op_sel_hi:[0,1,1]
	v_pk_fma_f32 v[58:59], v[42:43], v[54:55], v[58:59] op_sel_hi:[0,1,1]
	ds_read_b128 v[54:57], v47 offset:38912
	s_waitcnt lgkmcnt(0)
	v_pk_fma_f32 v[60:61], v[26:27], v[56:57], v[60:61] op_sel_hi:[0,1,1]
	v_pk_fma_f32 v[26:27], v[26:27], v[54:55], v[58:59] op_sel_hi:[0,1,1]
	ds_read_b128 v[54:57], v47 offset:39040
	s_waitcnt lgkmcnt(0)
; template <int MIX>
; __device__ __forceinline__ void scan_part(const Params& p, const int layer, const int smp, const int b0, const int bstep, const int bend, const int h, const int part, char* lds, const int tid) {
;     ...
;         for (int r = 0; r < 16; ++r) xg += lr[r] * *(const f32x4*)(wgl + r * 32 + sub * 4);
;         f32x4 dd;
; #pragma unroll
;         for (int i = 0; i < 4; ++i) { const float ls = fminf(xg[i], 0.f) - __logf(1.0f + __expf(-fabsf(xg[i]))); dd[i] = __expf(ls * 0.0625f); }
;         *(f32x4*)(dst + sub * 4) = (f32x4){q0 * sc, q1 * sc, q2 * sc, q3 * sc};
;         *(f32x4*)(dst + 64 + sub * 4) = (f32x4){k0, k1, k2, k3};
;         *(f32x4*)(dst + 128 + sub * 4) = dd;
	v_pk_fma_f32 v[56:57], v[24:25], v[56:57], v[60:61] op_sel_hi:[0,1,1]
	v_pk_fma_f32 v[54:55], v[24:25], v[54:55], v[26:27] op_sel_hi:[0,1,1]
	ds_read_b128 v[24:27], v47 offset:39168
	s_waitcnt lgkmcnt(0)
	v_pk_fma_f32 v[26:27], v[22:23], v[26:27], v[56:57] op_sel_hi:[0,1,1]
	v_pk_fma_f32 v[54:55], v[22:23], v[24:25], v[54:55] op_sel_hi:[0,1,1]
	ds_read_b128 v[22:25], v47 offset:39296
	s_waitcnt lgkmcnt(0)
	v_pk_fma_f32 v[24:25], v[20:21], v[24:25], v[26:27] op_sel_hi:[0,1,1]
	v_pk_fma_f32 v[20:21], v[20:21], v[22:23], v[54:55] op_sel_hi:[0,1,1]
	v_min_f32_e32 v19, 0, v20
	v_mul_f32_e64 v20, |v20|, s44
	v_exp_f32_e32 v20, v20
	v_lshlrev_b32_e32 v26, 16, v35
	v_and_b32_e32 v27, 0xffff0000, v35
	v_add_f32_e32 v20, 1.0, v20
	v_cmp_gt_f32_e32 vcc, s92, v20
	s_nop 1
	v_cndmask_b32_e64 v22, 0, 32, vcc
	v_ldexp_f32 v20, v20, v22
	v_log_f32_e32 v20, v20
	s_nop 0
	v_mul_f32_e32 v22, 0x3f317217, v20
	v_fma_f32 v22, v20, s45, -v22
	v_fmac_f32_e32 v22, 0x3377d1cf, v20
	v_fmac_f32_e32 v22, 0x3f317217, v20
	v_cmp_lt_f32_e64 s[40:41], |v20|, s46
	s_nop 1
	v_cndmask_b32_e64 v20, v20, v22, s[40:41]
	v_cndmask_b32_e32 v22, 0, v163, vcc
	v_sub_f32_e32 v20, v20, v22
	v_sub_f32_e32 v19, v19, v20
	v_mul_f32_e32 v19, 0x3d800000, v19
	v_mul_f32_e32 v19, 0x3fb8aa3b, v19
	v_exp_f32_e32 v20, v19
	v_min_f32_e32 v19, 0, v21
	v_mul_f32_e64 v21, |v21|, s44
	v_exp_f32_e32 v21, v21
	s_nop 0
	v_add_f32_e32 v21, 1.0, v21
	v_cmp_gt_f32_e32 vcc, s92, v21
	s_nop 1
	v_cndmask_b32_e64 v22, 0, 32, vcc
	v_ldexp_f32 v21, v21, v22
	v_log_f32_e32 v21, v21
	s_nop 0
	v_mul_f32_e32 v22, 0x3f317217, v21
	v_fma_f32 v22, v21, s45, -v22
	v_fmac_f32_e32 v22, 0x3377d1cf, v21
	v_fmac_f32_e32 v22, 0x3f317217, v21
	v_cmp_lt_f32_e64 s[40:41], |v21|, s46
	s_nop 1
	v_cndmask_b32_e64 v21, v21, v22, s[40:41]
	v_cndmask_b32_e32 v22, 0, v163, vcc
	v_sub_f32_e32 v21, v21, v22
	v_mul_f32_e64 v22, |v24|, s44
	v_exp_f32_e32 v22, v22
	v_sub_f32_e32 v19, v19, v21
	v_mul_f32_e32 v19, 0x3d800000, v19
	v_mul_f32_e32 v19, 0x3fb8aa3b, v19
	v_add_f32_e32 v22, 1.0, v22
	v_cmp_gt_f32_e32 vcc, s92, v22
	v_exp_f32_e32 v21, v19
	v_min_f32_e32 v19, 0, v24
	v_cndmask_b32_e64 v23, 0, 32, vcc
	v_ldexp_f32 v22, v22, v23
	v_log_f32_e32 v22, v22
	s_nop 0
	v_mul_f32_e32 v23, 0x3f317217, v22
	v_fma_f32 v23, v22, s45, -v23
	v_fmac_f32_e32 v23, 0x3377d1cf, v22
	v_fmac_f32_e32 v23, 0x3f317217, v22
	v_cmp_lt_f32_e64 s[40:41], |v22|, s46
	s_nop 1
	v_cndmask_b32_e64 v22, v22, v23, s[40:41]
	v_cndmask_b32_e32 v23, 0, v163, vcc
	v_sub_f32_e32 v22, v22, v23
	v_mul_f32_e64 v23, |v25|, s44
	v_exp_f32_e32 v23, v23
	v_sub_f32_e32 v19, v19, v22
	v_mul_f32_e32 v19, 0x3d800000, v19
	v_mul_f32_e32 v19, 0x3fb8aa3b, v19
	v_add_f32_e32 v23, 1.0, v23
	v_cmp_gt_f32_e32 vcc, s92, v23
	v_exp_f32_e32 v22, v19
	v_min_f32_e32 v19, 0, v25
	v_cndmask_b32_e64 v24, 0, 32, vcc
	v_ldexp_f32 v23, v23, v24
	v_log_f32_e32 v23, v23
	v_and_b32_e32 v25, 0xffff0000, v34
	v_mul_f32_e32 v24, 0x3f317217, v23
	v_fma_f32 v24, v23, s45, -v24
	v_fmac_f32_e32 v24, 0x3377d1cf, v23
	v_fmac_f32_e32 v24, 0x3f317217, v23
	v_cmp_lt_f32_e64 s[40:41], |v23|, s46
	s_nop 1
	v_cndmask_b32_e64 v23, v23, v24, s[40:41]
	v_cndmask_b32_e32 v24, 0, v163, vcc
	v_sub_f32_e32 v23, v23, v24
	v_sub_f32_e32 v19, v19, v23
	v_mul_f32_e32 v19, 0x3d800000, v19
	v_mul_f32_e32 v19, 0x3fb8aa3b, v19
	v_exp_f32_e32 v23, v19
	v_lshlrev_b32_e32 v24, 16, v34
	s_mov_b32 s40, 0x3e3504f3
	v_pk_mul_f32 v[26:27], v[26:27], s[40:41] op_sel_hi:[1,0]
	v_pk_mul_f32 v[24:25], v[24:25], s[40:41] op_sel_hi:[1,0]
	v_and_b32_e32 v19, 0xffff0000, v37
	ds_write_b128 v49, v[24:27]
	ds_write_b128 v49, v[16:19] offset:256
	ds_write_b128 v49, v[20:23] offset:512

; __device__ __forceinline__ unsigned pk2(float lo, float hi) { const f32x2_t v = {lo, hi}; const bf16x2_t b = __builtin_convertvector(v, bf16x2_t); return __builtin_bit_cast(unsigned, b); }
; __device__ __forceinline__ float red8d(float x) { x += dpp_x1(x); x += dpp_x2(x); x += dpp_hm(x); return x; }
; template <int MIX>
; __device__ __forceinline__ void scan_part(const Params& p, const int layer, const int smp, const int b0, const int bstep, const int bend, const int h, const int part, char* lds, const int tid) {
;     ...
;     __syncthreads();
;     if (valid) {
;       float o[VN];
; #pragma unroll
;       for (int i = 0; i < VN; ++i) o[i] = obuf[tt * CW + sub * VN + i];
;       float s1 = 0.f, s2 = 0.f;
; #pragma unroll
;       for (int i = 0; i < VN; ++i) { s1 += o[i]; s2 += o[i] * o[i]; }
;       s1 = red8d(s1); s2 = red8d(s2);
;       if (VN == 4) { uint2 o2; o2.x = pk2(o[0], o[1]); o2.y = pk2(o[2 % VN], o[3 % VN]); *(uint2*)(Ob + (size_t)(t0 + tt) * 1024 + sub * 4) = o2; }
;       else *(unsigned*)(Ob + (size_t)(t0 + tt) * 1024 + sub * 2) = pk2(o[0], o[1]);
;       if (sub == 0) *(float2*)(PS + (size_t)(t0 + tt) * 128) = make_float2(s1, s2);
;     }
.LBB0_362:
	s_waitcnt vmcnt(0) lgkmcnt(0)
	s_barrier
	s_and_saveexec_b64 s[42:43], s[38:39]
	s_cbranch_execz .LBB0_351
	ds_read_b128 v[20:23], v53 offset:32768
	s_waitcnt lgkmcnt(0)
	v_add_f32_e32 v19, 0, v20
	v_mul_f32_e32 v18, v20, v20
	v_mov_b32_e32 v16, v20
	v_mov_b32_e32 v17, v22
	v_add_f32_e32 v24, v19, v21
	v_fmac_f32_e32 v18, v21, v21
	v_mov_b32_e32 v25, v23
	v_pk_fma_f32 v[16:17], v[16:17], v[16:17], v[18:19] op_sel_hi:[1,1,0]
	v_pk_add_f32 v[18:19], v[24:25], v[22:23]
	v_pk_mul_f32 v[24:25], v[22:23], v[22:23]
	v_mov_b32_e32 v16, v23
	v_mov_b32_e32 v19, v25
	v_pk_add_f32 v[16:17], v[18:19], v[16:17]
	v_cvt_pk_bf16_f32 v24, v20, v21
	v_add_u32_e32 v20, s27, v45
	v_mov_b32_dpp v18, v16 quad_perm:[1,0,3,2] row_mask:0xf bank_mask:0xf bound_ctrl:1
	v_mov_b32_dpp v19, v17 quad_perm:[1,0,3,2] row_mask:0xf bank_mask:0xf bound_ctrl:1
	v_pk_add_f32 v[16:17], v[16:17], v[18:19]
	v_ashrrev_i32_e32 v21, 31, v20
	v_cvt_pk_bf16_f32 v25, v22, v23
	v_mov_b32_dpp v18, v16 quad_perm:[2,3,0,1] row_mask:0xf bank_mask:0xf bound_ctrl:1
	v_mov_b32_dpp v19, v17 quad_perm:[2,3,0,1] row_mask:0xf bank_mask:0xf bound_ctrl:1
	v_pk_add_f32 v[16:17], v[16:17], v[18:19]
	v_lshlrev_b64 v[22:23], 11, v[20:21]
	v_lshl_add_u64 v[22:23], v[38:39], 0, v[22:23]
	v_mov_b32_dpp v18, v16 row_half_mirror row_mask:0xf bank_mask:0xf bound_ctrl:1
	v_mov_b32_dpp v19, v17 row_half_mirror row_mask:0xf bank_mask:0xf bound_ctrl:1
	global_store_dwordx2 v[22:23], v[24:25], off offset:1024
	s_and_b64 exec, exec, s[36:37]
	s_cbranch_execz .LBB0_351
	v_lshlrev_b64 v[20:21], 9, v[20:21]
	v_lshl_add_u64 v[20:21], s[34:35], 0, v[20:21]
	v_pk_add_f32 v[16:17], v[16:17], v[18:19]
	global_store_dwordx2 v[20:21], v[16:17], off
	s_branch .LBB0_351

;   __device__ __forceinline__ const float* I(int i) const { return (const float*)(const GAS float*)in[i]; }
; __device__ __forceinline__ float sigmoidf_(float x) { return __builtin_amdgcn_rcpf(1.0f + __expf(-x)); }
; template <int MIX>
; __device__ __forceinline__ void scan_part(const Params& p, const int layer, const int smp, const int b0, const int bstep, const int bend, const int h, const int part, char* lds, const int tid) {
;     ...
;   } else if (MIX == 1) {
; #pragma unroll
;     for (int i = 0; i < 8; ++i) {
;       const int d = h * 64 + sub * 8 + i;
;       c8[i] = (layer == 0) ? 1.0f : sigmoidf_(p.I(15)[d] - p.I(15)[256 + d]);
;     }
;     ...
;   __syncthreads();
;   int ntok_last = 0;
;   for (int t0 = 0; t0 < T; t0 += 32) {
.LBB0_386:
	s_or_b64 exec, exec, s[2:3]
	s_lshl_b64 s[2:3], s[42:43], 11
	s_add_u32 s2, s72, s2
	s_addc_u32 s3, s73, s3
	s_lshl_b32 s29, s29, 1
	s_add_u32 s38, s2, s29
	s_addc_u32 s39, s3, 0
	s_lshl_b32 s40, s23, 1
	s_add_u32 s38, s38, s40
	s_mul_hi_u32 s41, s42, 0xfffffa00
	s_addc_u32 s39, s39, 0
	s_mul_i32 s40, s42, 0xfffffa00
	v_writelane_b32 v254, s42, 17
	s_sub_i32 s41, s41, s42
	s_add_u32 s2, s2, s40
	s_addc_u32 s3, s3, s41
	s_lshl_b32 s40, s25, 5
	v_lshrrev_b32_e32 v13, 3, v130
	s_add_u32 s2, s2, s40
	v_bfi_b32 v60, -8, v59, v13
	v_lshlrev_b32_e32 v13, 2, v12
	s_addc_u32 s3, s3, 0
	s_lshl_b32 s26, s26, 3
	v_lshl_or_b32 v64, v59, 10, v13
	s_add_u32 s2, s2, s26
	v_lshlrev_b32_e32 v12, 1, v12
	v_mov_b32_e32 v13, v3
	v_bfe_u32 v14, v130, 3, 3
	s_addc_u32 s3, s3, 0
	v_lshl_add_u64 v[48:49], s[38:39], 0, v[12:13]
	v_lshlrev_b32_e32 v12, 2, v59
	s_add_u32 s2, s2, 0x2255180
	v_and_b32_e32 v12, 0xffffffe0, v12
	v_lshlrev_b32_e32 v14, 2, v14
	v_lshlrev_b32_e32 v61, 2, v58
	v_lshlrev_b32_e32 v63, 4, v57
	s_addc_u32 s3, s3, 0
	v_lshl_add_u32 v13, v57, 7, v12
	v_or_b32_e32 v12, v12, v14
	v_sub_u32_e32 v15, v61, v63
	v_lshlrev_b32_e32 v16, 7, v59
	s_add_u32 s34, s34, s29
	v_or_b32_e32 v13, v13, v14
	v_add_u32_e32 v66, 0x700, v12
	v_mov_b32_e32 v12, 0x400
	v_lshlrev_b32_e32 v62, 2, v60
	v_cmp_eq_u32_e64 s[36:37], 0, v57
	v_writelane_b32 v254, s43, 18
	s_addc_u32 s35, s35, 0
	v_add_u32_e32 v65, 0x7d00, v13
	v_lshl_or_b32 v67, v57, 5, v12
	v_add_u32_e32 v68, v15, v16
	v_mov_b32_e32 v43, v42
	v_mov_b32_e32 v50, v42
	v_mov_b32_e32 v51, v42
	v_mov_b32_e32 v52, v42
	v_mov_b32_e32 v53, v42
	v_mov_b32_e32 v54, v42
	v_mov_b32_e32 v55, v42
	s_waitcnt vmcnt(0)
	s_barrier
	s_branch .LBB0_388

; __device__ __forceinline__ float sigmoidf_(float x) { return __builtin_amdgcn_rcpf(1.0f + __expf(-x)); }
; __device__ __forceinline__ float siluf_(float x) { return x * __builtin_amdgcn_rcpf(1.0f + __expf(-x)); }
; template <int MIX>
; __device__ __forceinline__ void scan_part(const Params& p, const int layer, const int smp, const int b0, const int bstep, const int bend, const int h, const int part, char* lds, const int tid) {
;     ...
;     } else if (MIX == 1) {
;       if (valid) {
;         float q[8], z[8]; unpack8(R0, q); unpack8(R1, z);
;         float kk[8], dd[8];
; #pragma unroll
;         for (int i = 0; i < 8; ++i) { q[i] = siluf_(q[i]); kk[i] = c8[i] * sigmoidf_(-z[i]); dd[i] = 1.0f - fminf(kk[i], 1.0f - 1e-6f); }
;         *(f32x4*)(dst + sub * 8) = (f32x4){q[0], q[1], q[2], q[3]}; *(f32x4*)(dst + sub * 8 + 4) = (f32x4){q[4], q[5], q[6], q[7]};
;         *(f32x4*)(dst + 64 + sub * 8) = (f32x4){kk[0], kk[1], kk[2], kk[3]}; *(f32x4*)(dst + 64 + sub * 8 + 4) = (f32x4){kk[4], kk[5], kk[6], kk[7]};
;         *(f32x4*)(dst + 128 + sub * 8) = (f32x4){dd[0], dd[1], dd[2], dd[3]}; *(f32x4*)(dst + 128 + sub * 8 + 4) = (f32x4){dd[4], dd[5], dd[6], dd[7]};
;       }
.LBB0_388:
	s_mov_b32 s26, s27
	s_sub_i32 s27, 0x810, s27
	s_min_u32 s29, s27, 32
	v_cmp_gt_i32_e64 s[38:39], s29, v59
	s_and_saveexec_b64 s[40:41], s[38:39]
	s_cbranch_execz .LBB0_390
	s_waitcnt vmcnt(2)
	v_lshlrev_b32_e32 v18, 16, v9
	v_mul_f32_e32 v18, 0x3fb8aa3b, v18
	v_lshlrev_b32_e32 v12, 16, v46
	v_and_b32_e32 v13, 0xffff0000, v46
	v_lshlrev_b32_e32 v14, 16, v47
	v_and_b32_e32 v15, 0xffff0000, v47
	v_exp_f32_e32 v19, v18
	ds_write_b128 v64, v[12:15] offset:768
	v_lshlrev_b32_e32 v14, 16, v4
	v_mul_f32_e32 v15, 0xbfb8aa3b, v14
	v_exp_f32_e32 v16, v15
	v_and_b32_e32 v15, 0xffff0000, v4
	v_lshlrev_b32_e32 v18, 16, v5
	v_mul_f32_e32 v17, 0xbfb8aa3b, v15
	v_mul_f32_e32 v20, 0xbfb8aa3b, v18
	v_add_f32_e32 v19, 1.0, v19
	v_exp_f32_e32 v17, v17
	v_exp_f32_e32 v22, v20
	v_rcp_f32_e32 v20, v19
	v_and_b32_e32 v19, 0xffff0000, v5
	v_mul_f32_e32 v23, 0xbfb8aa3b, v19
	v_exp_f32_e32 v23, v23
	v_and_b32_e32 v21, 0xffff0000, v9
	v_add_f32_e32 v16, 1.0, v16
	v_add_f32_e32 v17, 1.0, v17
	v_mul_f32_e32 v21, 0x3fb8aa3b, v21
	v_rcp_f32_e32 v16, v16
	v_rcp_f32_e32 v17, v17
	v_exp_f32_e32 v21, v21
	v_add_f32_e32 v22, 1.0, v22
	v_add_f32_e32 v23, 1.0, v23
	v_rcp_f32_e32 v22, v22
	v_rcp_f32_e32 v23, v23
	v_lshlrev_b32_e32 v24, 16, v10
	v_pk_mul_f32 v[16:17], v[16:17], v[14:15]
	v_add_f32_e32 v14, 1.0, v21
	v_rcp_f32_e32 v21, v14
	v_mul_f32_e32 v14, 0x3fb8aa3b, v24
	v_pk_mul_f32 v[18:19], v[22:23], v[18:19]
	v_exp_f32_e32 v22, v14
	v_pk_mul_f32 v[14:15], v[36:37], v[20:21]
	v_and_b32_e32 v25, 0xffff0000, v10
	v_and_b32_e32 v23, 0xffff0000, v6
	v_add_f32_e32 v20, 1.0, v22
	v_lshlrev_b32_e32 v22, 16, v6
	v_mul_f32_e32 v21, 0xbfb8aa3b, v22
	v_exp_f32_e32 v21, v21
	v_mul_f32_e32 v24, 0x3fb8aa3b, v25
	v_exp_f32_e32 v24, v24
	v_lshlrev_b32_e32 v26, 16, v11
	v_add_f32_e32 v25, 1.0, v21
	v_mul_f32_e32 v21, 0xbfb8aa3b, v23
	v_exp_f32_e32 v27, v21
	v_mul_f32_e32 v26, 0x3fb8aa3b, v26
	v_add_f32_e32 v21, 1.0, v24
	v_rcp_f32_e32 v24, v25
	v_add_f32_e32 v25, 1.0, v27
	v_exp_f32_e32 v27, v26
	v_lshlrev_b32_e32 v26, 16, v7
	v_lshlrev_b32_e32 v12, 16, v8
	v_and_b32_e32 v13, 0xffff0000, v8
	v_mul_f32_e32 v28, 0xbfb8aa3b, v26
	v_add_f32_e32 v27, 1.0, v27
	v_mul_f32_e32 v12, 0x3fb8aa3b, v12
	v_and_b32_e32 v29, 0xffff0000, v11
	v_mul_f32_e32 v13, 0x3fb8aa3b, v13
	v_exp_f32_e32 v30, v28
	v_rcp_f32_e32 v28, v27
	v_and_b32_e32 v27, 0xffff0000, v7
	v_exp_f32_e32 v12, v12
	v_exp_f32_e32 v13, v13
	v_mul_f32_e32 v31, 0xbfb8aa3b, v27
	v_mul_f32_e32 v29, 0x3fb8aa3b, v29
	v_exp_f32_e32 v31, v31
	v_exp_f32_e32 v29, v29
	v_add_f32_e32 v12, 1.0, v12
	v_add_f32_e32 v13, 1.0, v13
	v_rcp_f32_e32 v12, v12
	v_rcp_f32_e32 v13, v13
	v_add_f32_e32 v30, 1.0, v30
	v_add_f32_e32 v31, 1.0, v31
	v_add_f32_e32 v29, 1.0, v29
	v_rcp_f32_e32 v20, v20
	v_rcp_f32_e32 v21, v21
	v_rcp_f32_e32 v25, v25
	v_rcp_f32_e32 v30, v30
	v_rcp_f32_e32 v31, v31
	v_rcp_f32_e32 v29, v29
	v_pk_mul_f32 v[12:13], v[0:1], v[12:13]
	v_min_f32_e32 v34, 0x3f7fffef, v14
	v_min_f32_e32 v32, 0x3f7fffef, v12
	v_min_f32_e32 v33, 0x3f7fffef, v13
	v_min_f32_e32 v35, 0x3f7fffef, v15
	v_pk_mul_f32 v[20:21], v[38:39], v[20:21]
	v_pk_mul_f32 v[24:25], v[24:25], v[22:23]
	v_pk_mul_f32 v[26:27], v[30:31], v[26:27]
	v_pk_mul_f32 v[22:23], v[40:41], v[28:29]
	v_add_u32_e32 v30, v64, v63
	v_min_f32_e32 v45, 0x3f7fffef, v20
	v_min_f32_e32 v56, 0x3f7fffef, v21
	v_min_f32_e32 v28, 0x3f7fffef, v22
	v_min_f32_e32 v29, 0x3f7fffef, v23
	ds_write_b128 v30, v[16:19]
	ds_write_b128 v30, v[24:27] offset:16
	ds_write_b128 v30, v[12:15] offset:256
	ds_write_b128 v30, v[20:23] offset:272
	v_sub_f32_e32 v15, 1.0, v35
	v_sub_f32_e32 v14, 1.0, v34
	v_sub_f32_e32 v13, 1.0, v33
	v_sub_f32_e32 v12, 1.0, v32
	ds_write_b128 v30, v[12:15] offset:512
	v_sub_f32_e32 v15, 1.0, v29
	v_sub_f32_e32 v14, 1.0, v28
	v_sub_f32_e32 v13, 1.0, v56
	v_sub_f32_e32 v12, 1.0, v45
	ds_write_b128 v30, v[12:15] offset:528

; __device__ __forceinline__ unsigned pk2(float lo, float hi) { const f32x2_t v = {lo, hi}; const bf16x2_t b = __builtin_convertvector(v, bf16x2_t); return __builtin_bit_cast(unsigned, b); }
; __device__ __forceinline__ float red8d(float x) { x += dpp_x1(x); x += dpp_x2(x); x += dpp_hm(x); return x; }
; template <int MIX>
; __device__ __forceinline__ void scan_part(const Params& p, const int layer, const int smp, const int b0, const int bstep, const int bend, const int h, const int part, char* lds, const int tid) {
;     ...
;     __syncthreads();
;     if (valid) {
;       float o[VN];
; #pragma unroll
;       for (int i = 0; i < VN; ++i) o[i] = obuf[tt * CW + sub * VN + i];
;       float s1 = 0.f, s2 = 0.f;
; #pragma unroll
;       for (int i = 0; i < VN; ++i) { s1 += o[i]; s2 += o[i] * o[i]; }
;       s1 = red8d(s1); s2 = red8d(s2);
;       if (VN == 4) { uint2 o2; o2.x = pk2(o[0], o[1]); o2.y = pk2(o[2 % VN], o[3 % VN]); *(uint2*)(Ob + (size_t)(t0 + tt) * 1024 + sub * 4) = o2; }
;       else *(unsigned*)(Ob + (size_t)(t0 + tt) * 1024 + sub * 2) = pk2(o[0], o[1]);
;       if (sub == 0) *(float2*)(PS + (size_t)(t0 + tt) * 128) = make_float2(s1, s2);
;     }
.LBB0_398:
	s_waitcnt vmcnt(0) lgkmcnt(0)
	s_barrier
	s_and_saveexec_b64 s[42:43], s[38:39]
	s_cbranch_execz .LBB0_387
	ds_read_b128 v[16:19], v68 offset:32768
	s_waitcnt lgkmcnt(0)
	v_add_f32_e32 v15, 0, v16
	v_mul_f32_e32 v14, v16, v16
	v_mov_b32_e32 v12, v16
	v_mov_b32_e32 v13, v18
	v_add_f32_e32 v15, v15, v17
	v_fmac_f32_e32 v14, v17, v17
	v_add_f32_e32 v20, v15, v18
	v_pk_fma_f32 v[12:13], v[12:13], v[12:13], v[14:15] op_sel_hi:[1,1,0]
	v_pk_mul_f32 v[14:15], v[18:19], v[18:19]
	v_mov_b32_e32 v12, v19
	v_mov_b32_e32 v21, v15
	v_pk_add_f32 v[12:13], v[20:21], v[12:13]
	v_cvt_pk_bf16_f32 v20, v16, v17
	v_add_u32_e32 v16, s26, v59
	v_mov_b32_dpp v14, v12 quad_perm:[1,0,3,2] row_mask:0xf bank_mask:0xf bound_ctrl:1
	v_mov_b32_dpp v15, v13 quad_perm:[1,0,3,2] row_mask:0xf bank_mask:0xf bound_ctrl:1
	v_pk_add_f32 v[12:13], v[12:13], v[14:15]
	v_ashrrev_i32_e32 v17, 31, v16
	v_cvt_pk_bf16_f32 v21, v18, v19
	v_mov_b32_dpp v14, v12 quad_perm:[2,3,0,1] row_mask:0xf bank_mask:0xf bound_ctrl:1
	v_mov_b32_dpp v15, v13 quad_perm:[2,3,0,1] row_mask:0xf bank_mask:0xf bound_ctrl:1
	v_pk_add_f32 v[12:13], v[12:13], v[14:15]
	v_lshlrev_b64 v[18:19], 11, v[16:17]
	v_lshl_add_u64 v[18:19], v[48:49], 0, v[18:19]
	v_mov_b32_dpp v14, v12 row_half_mirror row_mask:0xf bank_mask:0xf bound_ctrl:1
	v_mov_b32_dpp v15, v13 row_half_mirror row_mask:0xf bank_mask:0xf bound_ctrl:1
	global_store_dwordx2 v[18:19], v[20:21], off offset:512
	s_and_b64 exec, exec, s[36:37]
	s_cbranch_execz .LBB0_387
	v_lshlrev_b64 v[16:17], 9, v[16:17]
	v_lshl_add_u64 v[16:17], s[2:3], 0, v[16:17]
	v_pk_add_f32 v[12:13], v[12:13], v[14:15]
	global_store_dwordx2 v[16:17], v[12:13], off
	s_branch .LBB0_387

;   __device__ __forceinline__ const float* I(int i) const { return (const float*)(const GAS float*)in[i]; }
; template <int MIX>
; __device__ __forceinline__ void scan_part(const Params& p, const int layer, const int smp, const int b0, const int bstep, const int bend, const int h, const int part, char* lds, const int tid) {
;     ...
;   if (MIX == 0) {
;     Aexp = __expf(p.I(12)[layer * 4 + h]); dtb = p.I(13)[layer * 4 + h];
; #pragma unroll
;     for (int j = 0; j < 4; ++j) {
;       const float* cwp = p.I(11) + (size_t)(layer * 4 + j) * 768;
; #pragma unroll
;       for (int i = 0; i < 8; ++i) { cwq[j][i] = cwp[h * 64 + sub * 8 + i]; cwk[j][i] = cwp[256 + h * 64 + sub * 8 + i]; }
;     }
;     for (int e = tid; e < 4 * CW; e += 256) { const int j = e / CW, r = e % CW; cwl[j * RS + 128 + r] = p.I(11)[(size_t)(layer * 4 + j) * 768 + 512 + h * 64 + part * CW + r]; }
;     ...
;   __syncthreads();
;   int ntok_last = 0;
;   for (int t0 = 0; t0 < T; t0 += 32) {
.LBB0_420:
	s_or_b64 exec, exec, s[38:39]
	v_readlane_b32 s48, v254, 17
	v_readlane_b32 s49, v254, 18
	s_lshl_b32 s26, s46, 3
	s_lshl_b64 s[42:43], s[48:49], 11
	s_add_u32 s29, s72, s42
	s_addc_u32 s44, s73, s43
	s_lshl_b64 s[42:43], s[34:35], 1
	s_add_u32 s29, s29, s42
	s_addc_u32 s43, s44, s43
	s_lshl_b32 s42, s25, 1
	s_add_u32 s42, s29, s42
	v_ashrrev_i32_e32 v0, 4, v130
	v_lshrrev_b32_e32 v1, 4, v130
	s_mov_b32 s27, s49
	v_lshlrev_b32_e32 v137, 2, v79
	v_lshlrev_b32_e32 v2, 2, v77
	s_addc_u32 s43, s43, 0
	s_lshl_b64 s[44:45], s[48:49], 9
	v_readlane_b32 s48, v253, 33
	v_bfi_b32 v134, -4, v0, v1
	v_sub_u32_e32 v140, v137, v2
	v_readlane_b32 s49, v253, 34
	s_add_u32 s29, s48, s44
	s_waitcnt vmcnt(17)
	v_mul_f32_e32 v2, 0x3fb8aa3b, v76
	v_lshlrev_b32_e32 v0, 2, v0
	v_bfe_u32 v80, v130, 4, 2
	v_and_b32_e32 v135, 15, v130
	s_addc_u32 s44, s49, s45
	s_lshl_b64 s[26:27], s[26:27], 2
	v_exp_f32_e32 v146, v2
	v_lshlrev_b32_e32 v2, 1, v79
	v_and_b32_e32 v0, -16, v0
	s_movk_i32 s23, 0x120
	s_add_u32 s26, s29, s26
	v_lshl_add_u64 v[100:101], s[42:43], 0, v[2:3]
	v_lshl_add_u32 v2, v135, 6, v0
	v_lshlrev_b32_e32 v76, 2, v80
	v_mul_lo_u32 v138, v131, s23
	s_addc_u32 s27, s44, s27
	s_lshl_b32 s29, s24, 3
	v_or_b32_e32 v2, v2, v76
	v_lshl_add_u32 v139, v78, 1, v138
	v_mul_i32_i24_e32 v1, -12, v77
	v_mad_u32_u24 v78, v77, 12, v140
	v_lshl_or_b32 v141, v131, 10, v137
	v_mul_u32_u24_e32 v81, 24, v77
	v_cmp_eq_u32_e64 s[38:39], 0, v77
	v_lshlrev_b32_e32 v145, 4, v135
	v_lshlrev_b32_e32 v77, 6, v131
	s_add_u32 s48, s26, s29
	v_add_u32_e32 v147, 0x7c80, v2
	v_or_b32_e32 v0, v0, v76
	v_mov_b32_e32 v2, v3
	v_lshlrev_b32_e32 v136, 2, v134
	s_mov_b32 s23, 0
	v_lshlrev_b32_e32 v142, 4, v131
	v_cmp_gt_i32_e64 s[40:41], 54, v130
	v_lshlrev_b32_e32 v143, 4, v130
	v_lshlrev_b32_e32 v144, 2, v135
	s_addc_u32 s49, s27, 0
	v_add_u32_e32 v148, 0x700, v0
	v_or_b32_e32 v149, 0x400, v145
	v_add_u32_e32 v150, v139, v1
	v_add_u32_e32 v151, v78, v138
	v_add_u32_e32 v152, v141, v81
	v_add_u32_e32 v153, v137, v77
	v_mov_b64_e32 v[104:105], v[2:3]
	v_mov_b64_e32 v[102:103], v[2:3]
	s_waitcnt vmcnt(0) lgkmcnt(0)
	s_barrier

; __device__ __forceinline__ float bflo(unsigned u) { return __uint_as_float(u << 16); }
; __device__ __forceinline__ float bfhi(unsigned u) { return __uint_as_float(u & 0xffff0000u); }
; template <int N, int RS>
; __device__ __forceinline__ void convN(const bf16_t* rawb, const float (&w)[4][N], int tt, int off, float (&x)[N]) {
; #pragma unroll
;   for (int i = 0; i < N; ++i) x[i] = 0.f;
; #pragma unroll
;   for (int j = 0; j < 4; ++j) {
;     float xv[N];
;     if (N == 8) { const uint4 rv = *(const uint4*)(rawb + (tt + j) * RS + off); unpack8(rv, xv); }
;     else if (N == 4) { const uint2 rv = *(const uint2*)(rawb + (tt + j) * RS + off); xv[0] = bflo(rv.x); xv[1] = bfhi(rv.x); xv[2 % N] = bflo(rv.y); xv[3 % N] = bfhi(rv.y); }
;     else { const unsigned rv = *(const unsigned*)(rawb + (tt + j) * RS + off); xv[0] = bflo(rv); xv[1] = bfhi(rv); }
; #pragma unroll
;     for (int i = 0; i < N; ++i) x[i] += w[j][i] * xv[i];
;   }
; template <int MIX>
; __device__ __forceinline__ void scan_part(const Params& p, const int layer, const int smp, const int b0, const int bstep, const int bend, const int h, const int part, char* lds, const int tid) {
;     ...
;       if (valid) {
;         float xq[8], xk[8], xv[VN];
;         { float cwv[4][VN];
; #pragma unroll
;           for (int j = 0; j < 4; ++j)
; #pragma unroll
;             for (int i = 0; i < VN; ++i) cwv[j][i] = cwl[j * RS + 128 + sub * VN + i];
;           convN<VN, RS>(rawb, cwv, tt, 128 + sub * VN, xv); }
;         convN<8, RS>(rawb, cwq, tt, sub * 8, xq);
;         convN<8, RS>(rawb, cwk, tt, 64 + sub * 8, xk);
.LBB0_423:
	s_or_b64 exec, exec, s[44:45]
	v_mov_b64_e32 v[240:241], v[68:69]
	v_mov_b64_e32 v[242:243], v[70:71]
	v_mov_b64_e32 v[244:245], v[72:73]
	v_mov_b64_e32 v[246:247], v[74:75]
	v_mov_b32_e32 v248, v97
	s_waitcnt lgkmcnt(0)
	s_barrier
	s_and_saveexec_b64 s[50:51], s[42:43]
	s_cbranch_execz .LBB0_426
	v_add_u32_e32 v2, v140, v138
	v_add_u32_e32 v0, 0x9200, v2
	v_add_u32_e32 v76, 0xbc00, v137
	ds_read2_b32 v[0:1], v0 offset0:64 offset1:136
	ds_read2_b64 v[76:79], v76 offset0:120 offset1:192
	v_add_u32_e32 v80, 0xc000, v137
	v_add_u32_e32 v2, 0x9400, v2
	ds_read2_b64 v[80:83], v80 offset0:136 offset1:208
	s_waitcnt lgkmcnt(2)
	v_lshlrev_b32_e32 v85, 16, v1
	v_lshlrev_b32_e32 v84, 16, v0
	s_waitcnt lgkmcnt(1)
	v_mov_b32_e32 v86, v76
	v_mov_b32_e32 v87, v78
	v_pk_mul_f32 v[84:85], v[86:87], v[84:85]
	v_and_b32_e32 v1, 0xffff0000, v1
	v_add_f32_e32 v76, 0, v84
	v_add_f32_e32 v86, v76, v85
	ds_read2_b32 v[84:85], v2 offset0:80 offset1:152
	v_and_b32_e32 v0, 0xffff0000, v0
	v_mov_b32_e32 v78, v77
	v_pk_mul_f32 v[0:1], v[78:79], v[0:1]
	s_waitcnt lgkmcnt(1)
	v_mov_b32_e32 v76, v80
	v_add_f32_e32 v0, 0, v0
	v_add_f32_e32 v2, v0, v1
	s_waitcnt lgkmcnt(0)
	v_lshlrev_b32_e32 v1, 16, v85
	v_lshlrev_b32_e32 v0, 16, v84
	v_mov_b32_e32 v77, v82
	v_pk_mul_f32 v[0:1], v[76:77], v[0:1]
	v_and_b32_e32 v77, 0xffff0000, v85
	v_and_b32_e32 v76, 0xffff0000, v84
	v_mov_b32_e32 v82, v81
	v_add_f32_e32 v0, v86, v0
	v_pk_mul_f32 v[76:77], v[82:83], v[76:77]
	v_add_f32_e32 v0, v0, v1
	v_add_f32_e32 v1, v2, v76
	v_add_f32_e32 v1, v1, v77
	ds_read_b128 v[78:81], v151 offset:37376
	ds_read_b128 v[82:85], v151 offset:37504
	ds_read_b128 v[86:89], v151 offset:37664
	ds_read_b128 v[90:93], v151 offset:37952
	v_mul_f32_e32 v2, 0xbfb8aa3b, v0
	ds_read_b128 v[174:177], v151 offset:38240
	v_exp_f32_e32 v2, v2
	v_mul_f32_e32 v76, 0xbfb8aa3b, v1
	v_exp_f32_e32 v77, v76
	s_waitcnt lgkmcnt(4)
	v_lshlrev_b32_e32 v154, 16, v80
	v_and_b32_e32 v155, 0xffff0000, v80
	v_lshlrev_b32_e32 v94, 16, v78
	v_and_b32_e32 v95, 0xffff0000, v78
	v_lshlrev_b32_e32 v106, 16, v79
	v_and_b32_e32 v107, 0xffff0000, v79
	v_lshlrev_b32_e32 v178, 16, v81
	v_and_b32_e32 v179, 0xffff0000, v81
	ds_read_b128 v[78:81], v151 offset:37792
	s_waitcnt lgkmcnt(3)
	v_lshlrev_b32_e32 v180, 16, v86
	v_and_b32_e32 v181, 0xffff0000, v86
	v_lshlrev_b32_e32 v182, 16, v87
	v_and_b32_e32 v183, 0xffff0000, v87
	v_lshlrev_b32_e32 v184, 16, v88
	v_and_b32_e32 v185, 0xffff0000, v88
	v_lshlrev_b32_e32 v186, 16, v89
	v_and_b32_e32 v187, 0xffff0000, v89
	ds_read_b128 v[86:89], v151 offset:38080
	s_waitcnt lgkmcnt(3)
	v_lshlrev_b32_e32 v188, 16, v90
	v_and_b32_e32 v189, 0xffff0000, v90
	v_lshlrev_b32_e32 v190, 16, v91
	v_and_b32_e32 v191, 0xffff0000, v91
	v_lshlrev_b32_e32 v192, 16, v92
	v_and_b32_e32 v193, 0xffff0000, v92
	v_lshlrev_b32_e32 v194, 16, v93
	v_and_b32_e32 v195, 0xffff0000, v93
	ds_read_b128 v[90:93], v151 offset:38368
	s_waitcnt vmcnt(2)
	v_pk_fma_f32 v[154:155], v[4:5], v[154:155], 0 op_sel_hi:[1,1,0]
	v_add_f32_e32 v2, 1.0, v2
	s_waitcnt vmcnt(2)
	v_pk_fma_f32 v[154:155], v[12:13], v[184:185], v[154:155]
	s_waitcnt lgkmcnt(3)
	v_lshlrev_b32_e32 v198, 16, v176
	v_and_b32_e32 v199, 0xffff0000, v176
	s_waitcnt vmcnt(2)
	v_pk_fma_f32 v[154:155], v[20:21], v[192:193], v[154:155]
	v_rcp_f32_e32 v76, v2
	v_add_f32_e32 v2, 1.0, v77
	s_waitcnt vmcnt(2)
	v_pk_fma_f32 v[154:155], v[28:29], v[198:199], v[154:155]
	v_rcp_f32_e32 v77, v2
	v_mul_f32_e32 v2, 0xbfb8aa3b, v154
	v_lshlrev_b32_e32 v202, 16, v84
	v_and_b32_e32 v203, 0xffff0000, v84
	s_waitcnt lgkmcnt(0)
	v_lshlrev_b32_e32 v214, 16, v92
	v_and_b32_e32 v215, 0xffff0000, v92
	v_exp_f32_e32 v2, v2
	v_mul_f32_e32 v92, 0xbfb8aa3b, v155
	v_lshlrev_b32_e32 v206, 16, v80
	v_and_b32_e32 v207, 0xffff0000, v80
	v_exp_f32_e32 v158, v92
	s_waitcnt vmcnt(2)
	v_pk_fma_f32 v[192:193], v[36:37], v[202:203], 0 op_sel_hi:[1,1,0]
	v_lshlrev_b32_e32 v210, 16, v88
	v_and_b32_e32 v211, 0xffff0000, v88
	s_waitcnt vmcnt(2)
	v_pk_fma_f32 v[192:193], v[44:45], v[206:207], v[192:193]
	v_add_f32_e32 v2, 1.0, v2
	s_waitcnt vmcnt(2)
	v_pk_fma_f32 v[192:193], v[52:53], v[210:211], v[192:193]
	v_rcp_f32_e32 v184, v2
	s_waitcnt vmcnt(2)
	v_pk_fma_f32 v[192:193], v[60:61], v[214:215], v[192:193]
	v_add_f32_e32 v2, 1.0, v158
	v_mul_f32_e32 v158, 0xbfb8aa3b, v192
	v_exp_f32_e32 v158, v158
	v_mul_f32_e32 v159, 0xbfb8aa3b, v193
	v_exp_f32_e32 v159, v159
	v_pk_fma_f32 v[178:179], v[6:7], v[178:179], 0 op_sel_hi:[1,1,0]
	v_lshlrev_b32_e32 v176, 16, v177
	v_pk_fma_f32 v[178:179], v[14:15], v[186:187], v[178:179]
	v_and_b32_e32 v177, 0xffff0000, v177
	v_rcp_f32_e32 v185, v2
	v_add_f32_e32 v2, 1.0, v158
	v_pk_fma_f32 v[178:179], v[22:23], v[194:195], v[178:179]
	v_rcp_f32_e32 v198, v2
	v_add_f32_e32 v2, 1.0, v159
	v_pk_fma_f32 v[176:177], v[30:31], v[176:177], v[178:179]
	v_rcp_f32_e32 v199, v2
	v_mul_f32_e32 v2, 0xbfb8aa3b, v176
	v_exp_f32_e32 v2, v2
	v_mul_f32_e32 v158, 0xbfb8aa3b, v177
	v_exp_f32_e32 v158, v158
	v_pk_fma_f32 v[94:95], v[8:9], v[94:95], 0 op_sel_hi:[1,1,0]
	v_lshlrev_b32_e32 v196, 16, v174
	v_pk_fma_f32 v[94:95], v[16:17], v[180:181], v[94:95]
	v_and_b32_e32 v197, 0xffff0000, v174
	v_add_f32_e32 v2, 1.0, v2
	v_pk_fma_f32 v[94:95], v[24:25], v[188:189], v[94:95]
	v_rcp_f32_e32 v186, v2
	v_add_f32_e32 v2, 1.0, v158
	v_pk_fma_f32 v[94:95], v[32:33], v[196:197], v[94:95]
	v_rcp_f32_e32 v187, v2
	v_mul_f32_e32 v2, 0xbfb8aa3b, v94
	v_exp_f32_e32 v2, v2
	v_mul_f32_e32 v158, 0xbfb8aa3b, v95
	v_exp_f32_e32 v158, v158
	v_pk_fma_f32 v[106:107], v[10:11], v[106:107], 0 op_sel_hi:[1,1,0]
	v_lshlrev_b32_e32 v174, 16, v175
	v_pk_fma_f32 v[106:107], v[18:19], v[182:183], v[106:107]
; __device__ __forceinline__ float bflo(unsigned u) { return __uint_as_float(u << 16); }
; __device__ __forceinline__ float sigmoidf_(float x) { return __builtin_amdgcn_rcpf(1.0f + __expf(-x)); }
; __device__ __forceinline__ float softplusf_(float x) { return fmaxf(x, 0.f) + __logf(1.0f + __expf(-fabsf(x))); }
; __device__ __forceinline__ float red8d(float x) { x += dpp_x1(x); x += dpp_x2(x); x += dpp_hm(x); return x; }
; template <int MIX>
; __device__ __forceinline__ void scan_part(const Params& p, const int layer, const int smp, const int b0, const int bstep, const int bend, const int h, const int part, char* lds, const int tid) {
;     ...
;         convN<8, RS>(rawb, cwq, tt, sub * 8, xq);
;         convN<8, RS>(rawb, cwk, tt, 64 + sub * 8, xk);
; #pragma unroll
;         for (int i = 0; i < VN; ++i) dst[192 + sub * VN + i] = xv[i];
;         float ssq = 0.f, ssk = 0.f;
; #pragma unroll
;         for (int i = 0; i < 8; ++i) { ssq += xq[i] * xq[i]; ssk += xk[i] * xk[i]; }
;         ssq = red8d(ssq); ssk = red8d(ssk);
;         const float rq = rsqrtf(ssq + 1e-6f) * 0.125f, rk = rsqrtf(ssk + 1e-6f);
;         float qk = 0.f;
; #pragma unroll
;         for (int i = 0; i < 8; ++i) { xq[i] *= rq; xk[i] *= rk; qk += xq[i] * xk[i]; }
;         qk = red8d(qk);
;         *(f32x4*)(dst + sub * 8) = (f32x4){xq[0], xq[1], xq[2], xq[3]}; *(f32x4*)(dst + sub * 8 + 4) = (f32x4){xq[4], xq[5], xq[6], xq[7]};
;         *(f32x4*)(dst + 64 + sub * 8) = (f32x4){xk[0], xk[1], xk[2], xk[3]}; *(f32x4*)(dst + 64 + sub * 8 + 4) = (f32x4){xk[4], xk[5], xk[6], xk[7]};
;         if (sub == 0) {
;           const float be = sigmoidf_(bflo(ex0)), al = bflo(ex1);
;           const float a = __expf(-Aexp * softplusf_(al + dtb));
;           *(f32x4*)(scal + tt * 4) = (f32x4){a, be, qk, 0.f};
	v_and_b32_e32 v175, 0xffff0000, v175
	v_pk_fma_f32 v[106:107], v[26:27], v[190:191], v[106:107]
	v_add_f32_e32 v2, 1.0, v2
	v_pk_fma_f32 v[106:107], v[34:35], v[174:175], v[106:107]
	v_rcp_f32_e32 v180, v2
	v_add_f32_e32 v2, 1.0, v158
	v_mul_f32_e32 v158, 0xbfb8aa3b, v106
	v_exp_f32_e32 v158, v158
	v_mul_f32_e32 v159, 0xbfb8aa3b, v107
	v_lshlrev_b32_e32 v84, 16, v85
	v_and_b32_e32 v85, 0xffff0000, v85
	v_exp_f32_e32 v159, v159
	v_lshlrev_b32_e32 v80, 16, v81
	v_and_b32_e32 v81, 0xffff0000, v81
	v_pk_fma_f32 v[84:85], v[38:39], v[84:85], 0 op_sel_hi:[1,1,0]
	v_lshlrev_b32_e32 v88, 16, v89
	v_and_b32_e32 v89, 0xffff0000, v89
	v_pk_fma_f32 v[80:81], v[46:47], v[80:81], v[84:85]
	v_lshlrev_b32_e32 v92, 16, v93
	v_and_b32_e32 v93, 0xffff0000, v93
	v_rcp_f32_e32 v181, v2
	v_add_f32_e32 v2, 1.0, v158
	v_pk_fma_f32 v[80:81], v[54:55], v[88:89], v[80:81]
	v_rcp_f32_e32 v174, v2
	v_add_f32_e32 v2, 1.0, v159
	v_pk_fma_f32 v[80:81], v[62:63], v[92:93], v[80:81]
	v_rcp_f32_e32 v175, v2
	v_mul_f32_e32 v2, 0xbfb8aa3b, v80
	v_exp_f32_e32 v2, v2
	v_mul_f32_e32 v84, 0xbfb8aa3b, v81
	v_exp_f32_e32 v89, v84
	v_lshlrev_b32_e32 v200, 16, v82
	v_and_b32_e32 v201, 0xffff0000, v82
	v_lshlrev_b32_e32 v204, 16, v78
	v_and_b32_e32 v205, 0xffff0000, v78
	v_add_f32_e32 v2, 1.0, v2
	v_pk_fma_f32 v[92:93], v[40:41], v[200:201], 0 op_sel_hi:[1,1,0]
	v_lshlrev_b32_e32 v82, 16, v83
	v_and_b32_e32 v83, 0xffff0000, v83
	v_lshlrev_b32_e32 v208, 16, v86
	v_and_b32_e32 v209, 0xffff0000, v86
	v_rcp_f32_e32 v88, v2
	v_add_f32_e32 v2, 1.0, v89
	v_pk_fma_f32 v[92:93], v[48:49], v[204:205], v[92:93]
	v_lshlrev_b32_e32 v78, 16, v79
	v_and_b32_e32 v79, 0xffff0000, v79
	v_lshlrev_b32_e32 v212, 16, v90
	v_and_b32_e32 v213, 0xffff0000, v90
	v_rcp_f32_e32 v89, v2
	v_pk_fma_f32 v[92:93], v[56:57], v[208:209], v[92:93]
	v_pk_fma_f32 v[82:83], v[42:43], v[82:83], 0 op_sel_hi:[1,1,0]
	v_lshlrev_b32_e32 v86, 16, v87
	v_and_b32_e32 v87, 0xffff0000, v87
	s_waitcnt vmcnt(2)
	v_pk_fma_f32 v[92:93], v[64:65], v[212:213], v[92:93]
	v_pk_fma_f32 v[78:79], v[50:51], v[78:79], v[82:83]
	v_lshlrev_b32_e32 v90, 16, v91
	v_and_b32_e32 v91, 0xffff0000, v91
	v_mul_f32_e32 v2, 0xbfb8aa3b, v92
	v_pk_fma_f32 v[78:79], v[58:59], v[86:87], v[78:79]
	v_exp_f32_e32 v2, v2
	v_mul_f32_e32 v158, 0xbfb8aa3b, v93
	v_pk_fma_f32 v[78:79], v[66:67], v[90:91], v[78:79]
	v_pk_mul_f32 v[106:107], v[106:107], v[174:175]
	v_exp_f32_e32 v158, v158
	v_pk_mul_f32 v[174:175], v[80:81], v[88:89]
	v_mul_f32_e32 v81, 0xbfb8aa3b, v78
	v_exp_f32_e32 v82, v81
	v_mul_f32_e32 v81, 0xbfb8aa3b, v79
	v_exp_f32_e32 v83, v81
	v_add_f32_e32 v2, 1.0, v2
	v_rcp_f32_e32 v80, v2
	v_add_f32_e32 v2, 1.0, v158
	v_rcp_f32_e32 v81, v2
	v_add_f32_e32 v2, 1.0, v82
	v_rcp_f32_e32 v82, v2
	v_add_f32_e32 v2, 1.0, v83
	v_rcp_f32_e32 v83, v2
	v_pk_mul_f32 v[94:95], v[94:95], v[180:181]
	v_pk_mul_f32 v[88:89], v[92:93], v[80:81]
	v_pk_mul_f32 v[180:181], v[94:95], v[94:95]
	v_pk_mul_f32 v[80:81], v[88:89], v[88:89]
	v_pk_mul_f32 v[90:91], v[78:79], v[82:83]
	v_pk_mul_f32 v[84:85], v[106:107], v[106:107]
	v_pk_mul_f32 v[78:79], v[90:91], v[90:91]
	v_mov_b32_e32 v82, v80
	v_mov_b32_e32 v83, v180
	v_mov_b32_e32 v180, v81
	v_pk_mul_f32 v[154:155], v[154:155], v[184:185]
	v_pk_mul_f32 v[192:193], v[192:193], v[198:199]
	v_pk_add_f32 v[80:81], v[82:83], v[180:181]
	v_mov_b32_e32 v82, v78
	v_mov_b32_e32 v83, v84
	v_pk_mul_f32 v[184:185], v[154:155], v[154:155]
	v_pk_mul_f32 v[178:179], v[192:193], v[192:193]
	v_pk_add_f32 v[80:81], v[80:81], v[82:83]
	v_mov_b32_e32 v84, v79
	v_pk_mul_f32 v[176:177], v[176:177], v[186:187]
	v_pk_add_f32 v[78:79], v[84:85], v[80:81]
	v_mov_b32_e32 v80, v178
	v_mov_b32_e32 v81, v184
	v_pk_mul_f32 v[182:183], v[176:177], v[176:177]
	v_pk_mul_f32 v[86:87], v[174:175], v[174:175]
	v_pk_add_f32 v[78:79], v[80:81], v[78:79]
	v_mov_b32_e32 v184, v179
	v_pk_add_f32 v[78:79], v[184:185], v[78:79]
	v_mov_b32_e32 v80, v86
	v_mov_b32_e32 v81, v182
	v_pk_add_f32 v[78:79], v[80:81], v[78:79]
	v_mov_b32_e32 v182, v87
	v_pk_add_f32 v[78:79], v[182:183], v[78:79]
	s_mov_b32 s44, 0x358637bd
	v_pk_mul_f32 v[0:1], v[0:1], v[76:77]
	v_mov_b32_dpp v81, v79 quad_perm:[1,0,3,2] row_mask:0xf bank_mask:0xf bound_ctrl:1
	v_mov_b32_dpp v80, v78 quad_perm:[1,0,3,2] row_mask:0xf bank_mask:0xf bound_ctrl:1
	v_pk_add_f32 v[78:79], v[78:79], v[80:81]
	ds_write_b64 v141, v[0:1] offset:768
	s_nop 0
	v_mov_b32_dpp v81, v79 quad_perm:[2,3,0,1] row_mask:0xf bank_mask:0xf bound_ctrl:1
	v_mov_b32_dpp v80, v78 quad_perm:[2,3,0,1] row_mask:0xf bank_mask:0xf bound_ctrl:1
	v_pk_add_f32 v[78:79], v[78:79], v[80:81]
	s_nop 1
	v_mov_b32_dpp v81, v79 row_half_mirror row_mask:0xf bank_mask:0xf bound_ctrl:1
	v_mov_b32_dpp v80, v78 row_half_mirror row_mask:0xf bank_mask:0xf bound_ctrl:1
	v_pk_add_f32 v[78:79], v[78:79], v[80:81]
	s_nop 0
	v_pk_add_f32 v[78:79], v[78:79], s[44:45] op_sel_hi:[1,0]
	s_nop 0
	v_mul_f32_e32 v2, 0x4b800000, v79
	v_cmp_gt_f32_e32 vcc, s92, v79
	s_nop 1
	v_cndmask_b32_e32 v2, v79, v2, vcc
	v_rsq_f32_e32 v2, v2
	s_nop 0
	v_mul_f32_e32 v0, 0x45800000, v2
	v_cndmask_b32_e32 v0, v2, v0, vcc
	v_mul_f32_e32 v0, 0x3e000000, v0
	v_pk_mul_f32 v[76:77], v[94:95], v[0:1] op_sel_hi:[1,0]
	v_mul_f32_e32 v1, 0x4b800000, v78
	v_cmp_gt_f32_e32 vcc, s92, v78
	s_nop 1
	v_cndmask_b32_e32 v1, v78, v1, vcc
	v_rsq_f32_e32 v1, v1
	s_nop 0
	v_pk_mul_f32 v[78:79], v[106:107], v[0:1] op_sel_hi:[1,0]
	v_pk_mul_f32 v[80:81], v[154:155], v[0:1] op_sel_hi:[1,0]
	v_pk_mul_f32 v[82:83], v[176:177], v[0:1] op_sel_hi:[1,0]
	v_mul_f32_e32 v0, 0x45800000, v1
	v_cndmask_b32_e32 v0, v1, v0, vcc
	v_pk_mul_f32 v[84:85], v[88:89], v[0:1] op_sel_hi:[1,0]
	s_nop 0
	v_pk_mul_f32 v[86:87], v[90:91], v[0:1] op_sel_hi:[1,0]
	s_nop 0
	v_pk_mul_f32 v[88:89], v[192:193], v[0:1] op_sel_hi:[1,0]
	s_nop 0
	v_pk_mul_f32 v[90:91], v[174:175], v[0:1] op_sel_hi:[1,0]
	ds_write_b128 v152, v[76:79]
	ds_write_b128 v152, v[80:83] offset:16
	ds_write_b128 v152, v[84:87] offset:256
	ds_write_b128 v152, v[88:91] offset:272
	s_and_b64 exec, exec, s[38:39]
	s_cbranch_execz .LBB0_426
	v_mov_b32_e32 v2, 0
	v_lshlrev_b32_e32 v0, 16, v133
	v_mul_f32_e32 v0, 0xbfb8aa3b, v0
	v_exp_f32_e32 v0, v0
	s_mov_b32 s27, 0xbfb8aa3b
	v_add_f32_e32 v0, 1.0, v0
	v_rcp_f32_e32 v1, v0
	v_lshlrev_b32_e32 v0, 16, v99
	v_add_f32_e32 v0, v132, v0
	v_max_f32_e32 v76, 0, v0
	v_mul_f32_e64 v0, |v0|, s27
	v_exp_f32_e32 v0, v0
	s_mov_b32 s27, 0x3f317217
	v_add_f32_e32 v0, 1.0, v0
	v_cmp_gt_f32_e32 vcc, s92, v0
	s_nop 1
	v_cndmask_b32_e64 v77, 0, 32, vcc
	v_ldexp_f32 v0, v0, v77
	v_log_f32_e32 v0, v0
	s_nop 0
	v_mul_f32_e32 v77, 0x3f317217, v0
	v_fma_f32 v77, v0, s27, -v77
	v_fmac_f32_e32 v77, 0x3377d1cf, v0
	s_mov_b32 s27, 0x7f800000
	v_fmac_f32_e32 v77, 0x3f317217, v0
	v_cmp_lt_f32_e64 s[44:45], |v0|, s27
	s_nop 1
	v_cndmask_b32_e64 v0, v0, v77, s[44:45]
	v_cndmask_b32_e32 v77, 0, v163, vcc
	v_sub_f32_e32 v0, v0, v77
	v_add_f32_e32 v0, v76, v0
	v_mul_f32_e32 v0, v0, v146
	v_mul_f32_e32 v0, 0xbfb8aa3b, v0
	v_exp_f32_e32 v0, v0
	ds_write_b128 v142, v[0:3] offset:36864
;   __device__ __forceinline__ unsigned char* W() const { return (unsigned char*)(GAS unsigned char*)ws; }
; template <int MIX, int VN> ...
;   if (t < T) {
;     const bf16_t* pr = Pb + (size_t)t * DINP;
;     const int vbase = (MIX == 0) ? 512 : (MIX == 1) ? 1544 : (MIX == 2) ? 2312 : 3352;
;     if (VN == 4) R2 = *(const uint2*)(pr + vbase + h * 64 + vcol);
;     else R2.x = *(const unsigned*)(pr + vbase + h * 64 + vcol);
;     if (MIX == 0) {
;       R0 = *(const uint4*)(pr + 0 + h * 64 + sub * 8); R1 = *(const uint4*)(pr + 256 + h * 64 + sub * 8);
;       ex0 = pr[768 + h]; ex1 = pr[772 + h];
;     } else if (MIX == 1) {
; template <int MIX>
; __device__ __forceinline__ void scan_part(const Params& p, const int layer, const int smp, const int b0, const int bstep, const int bend, const int h, const int part, char* lds, const int tid) {
;     ...
;     if (MIX == 0 && t0 + 32 < T) {
;       if (tid < 3 * RS / 8) { const uint4 v = *(const uint4*)(rawb + 32 * RS + tid * 8); *(uint4*)(rawb + tid * 8) = v; }
;     }
;     if (t0 + 32 < T) load_chunk_fn<MIX, VN>(p.W(), Pb, t0 + 32 + tt, T, h, vcol, sub, posb, R0, R1, R2, R4, R5, ex0, ex1);
;     {
;       StepIn<MIX, KPL> sa, sb;
;       float osave = 0.f;
;       load_step<MIX, KPL>(qkdv, scal, 0, kg, col, sa);
.LBB0_426:
	s_or_b64 exec, exec, s[50:51]
	s_cmpk_lt_u32 s23, 0x7f0
	s_cselect_b64 s[50:51], -1, 0
	s_cmpk_gt_u32 s23, 0x7ef
	s_cselect_b64 s[44:45], -1, 0
	s_and_b64 s[56:57], s[40:41], s[50:51]
	s_waitcnt lgkmcnt(0)
	s_barrier
	v_mov_b32_e32 v211, v145
	v_mov_b32_e32 v212, v136
	v_mov_b32_e32 v213, 0
	v_and_b32_e32 v214, 3, v135
	v_lshl_add_u32 v214, v214, 6, v136
	ds_read_b128 v[92:95], v211 offset:256
	ds_read_b64 v[106:107], v213 offset:36864
	ds_read_b32 v182, v212 offset:768
	ds_read_b128 v[76:79], v211
	ds_read_b128 v[174:177], v211 offset:1280
	ds_read_b64 v[154:155], v213 offset:36880
	ds_read_b32 v188, v212 offset:1792
	ds_read_b128 v[80:83], v211 offset:1024
	s_andn2_b64 vcc, exec, s[50:51]
	s_add_i32 s27, s23, 32
	s_cbranch_vccnz .LBB0_432
	v_add_u32_e32 v0, s27, v131
	s_movk_i32 s29, 0x810
	v_cmp_gt_i32_e32 vcc, s29, v0
	s_and_saveexec_b64 s[50:51], vcc
	s_cbranch_execz .LBB0_431
	s_waitcnt vmcnt(2)
	v_mov_b64_e32 v[68:69], s[2:3]
	v_mad_i64_i32 v[0:1], s[52:53], v0, s68, v[68:69]
	v_lshl_add_u64 v[68:69], s[34:35], 1, v[0:1]
	v_mov_b32_e32 v97, v3
	s_waitcnt vmcnt(2)
	v_mov_b32_e32 v99, v3
	v_readlane_b32 s52, v254, 17
	v_lshl_add_u64 v[70:71], v[68:69], 0, v[96:97]
	v_lshl_add_u64 v[72:73], v[68:69], 0, v[98:99]
	v_readlane_b32 s53, v254, 18
	s_lshl_b32 s52, s46, 1
	global_load_dword v97, v[70:71], off offset:1024
	s_nop 0
	global_load_dwordx4 v[68:71], v[72:73], off
	v_lshl_add_u64 v[0:1], v[0:1], 0, s[52:53]
	global_load_dwordx4 v[72:75], v[72:73], off offset:512
	s_nop 0
	global_load_ushort v133, v[0:1], off offset:1536
	global_load_ushort v99, v[0:1], off offset:1544
	s_mov_b32 s29, s53
	v_writelane_b32 v254, s28, 17
	s_nop 1
	v_writelane_b32 v254, s29, 18

; __device__ __forceinline__ unsigned pk2(float lo, float hi) { const f32x2_t v = {lo, hi}; const bf16x2_t b = __builtin_convertvector(v, bf16x2_t); return __builtin_bit_cast(unsigned, b); }
; __device__ __forceinline__ float red8d(float x) { x += dpp_x1(x); x += dpp_x2(x); x += dpp_hm(x); return x; }
; template <int MIX>
; __device__ __forceinline__ void scan_part(const Params& p, const int layer, const int smp, const int b0, const int bstep, const int bend, const int h, const int part, char* lds, const int tid) {
;     ...
;     __syncthreads();
;     if (valid) {
;       float o[VN];
; #pragma unroll
;       for (int i = 0; i < VN; ++i) o[i] = obuf[tt * CW + sub * VN + i];
;       float s1 = 0.f, s2 = 0.f;
; #pragma unroll
;       for (int i = 0; i < VN; ++i) { s1 += o[i]; s2 += o[i] * o[i]; }
;       s1 = red8d(s1); s2 = red8d(s2);
;       if (VN == 4) { uint2 o2; o2.x = pk2(o[0], o[1]); o2.y = pk2(o[2 % VN], o[3 % VN]); *(uint2*)(Ob + (size_t)(t0 + tt) * 1024 + sub * 4) = o2; }
;       else *(unsigned*)(Ob + (size_t)(t0 + tt) * 1024 + sub * 2) = pk2(o[0], o[1]);
;       if (sub == 0) *(float2*)(PS + (size_t)(t0 + tt) * 128) = make_float2(s1, s2);
;     }
.LBB0_436:
	s_waitcnt vmcnt(0) lgkmcnt(0)
	s_barrier
	s_and_saveexec_b64 s[50:51], s[42:43]
	s_cbranch_execz .LBB0_439
	ds_read_b64 v[78:79], v153 offset:32768
	s_waitcnt lgkmcnt(0)
	v_pk_mul_f32 v[76:77], v[78:79], v[78:79]
	v_add_f32_e32 v0, 0, v78
	v_mov_b32_e32 v1, v77
	v_pk_mov_b32 v[76:77], v[78:79], v[76:77] op_sel:[1,0]
	v_cvt_pk_bf16_f32 v2, v78, v79
	v_pk_add_f32 v[0:1], v[0:1], v[76:77]
	v_add_u32_e32 v78, s23, v131
	v_ashrrev_i32_e32 v79, 31, v78
	v_mov_b32_dpp v76, v0 quad_perm:[1,0,3,2] row_mask:0xf bank_mask:0xf bound_ctrl:1
	v_mov_b32_dpp v77, v1 quad_perm:[1,0,3,2] row_mask:0xf bank_mask:0xf bound_ctrl:1
	v_pk_add_f32 v[0:1], v[0:1], v[76:77]
	v_lshlrev_b64 v[80:81], 11, v[78:79]
	v_lshl_add_u64 v[80:81], v[100:101], 0, v[80:81]
	v_mov_b32_dpp v76, v0 quad_perm:[2,3,0,1] row_mask:0xf bank_mask:0xf bound_ctrl:1
	v_mov_b32_dpp v77, v1 quad_perm:[2,3,0,1] row_mask:0xf bank_mask:0xf bound_ctrl:1
	v_pk_add_f32 v[0:1], v[0:1], v[76:77]
	global_store_dword v[80:81], v2, off
	s_nop 0
	v_mov_b32_dpp v76, v0 row_half_mirror row_mask:0xf bank_mask:0xf bound_ctrl:1
	v_mov_b32_dpp v77, v1 row_half_mirror row_mask:0xf bank_mask:0xf bound_ctrl:1
	s_and_b64 exec, exec, s[38:39]
	s_cbranch_execz .LBB0_439
	v_lshlrev_b64 v[78:79], 9, v[78:79]
	v_lshl_add_u64 v[78:79], s[48:49], 0, v[78:79]
	v_pk_add_f32 v[0:1], v[0:1], v[76:77]
	global_store_dwordx2 v[78:79], v[0:1], off
